# MLA loop: address register round trips removed (four 64-bit moves per iteration)
# baseline (speedup 1.0000x reference)
; DI f32x16 mfma32(bf16x8 a, bf16x8 b, f32x16 c) { return __builtin_amdgcn_mfma_f32_32x32x16_bf16(a, b, c, 0, 0, 0); }
; DI void attn_mla_unit(const Params& p, int b, int h, int qb, char* smem, bool pre, int nh, bool has_next) {
;     ...
;         for (int s = 0; s < 6; ++s) {
;           kf[2 * s] = *(const bf16x8*)(ks + (sub * 64 + r32) * KR + (s * 16 + hh * 8) * 2);
;           kf[2 * s + 1] = *(const bf16x8*)(ks + (sub * 64 + 32 + r32) * KR + (s * 16 + hh * 8) * 2);
;         }
;         __builtin_amdgcn_sched_barrier(0); __builtin_amdgcn_s_setprio(1);
; #pragma unroll
;         for (int s = 0; s < 6; ++s) { s0 = mfma32(kf[2 * s], qf[s], s0); s1 = mfma32(kf[2 * s + 1], qf[s], s1); }
;       __builtin_amdgcn_s_setprio(0);
; }
;       float alpha; bf16x8 pf[4];
;       const bool resc = softmax_tile(s0, s1, m, l, alpha, pf, lane, (kt == 0) && (sub == 0), (sub == 0) && ((kt & 3) == 0));
;       {
;         bf16x8 vf[8];
; #pragma unroll
;         for (int s = 0; s < 4; ++s) { vf[2 * s] = ld_vfrag_tr(vs, vbase, VR, sub * 64 + 16 * s, 0); vf[2 * s + 1] = ld_vfrag_tr(vs, vbase, VR, sub * 64 + 16 * s, 32); }
;         __builtin_amdgcn_sched_barrier(0); __builtin_amdgcn_s_setprio(1);
; #pragma unroll
;         for (int s = 0; s < 4; ++s) { O0 = mfma32(vf[2 * s], pf[s], O0); O1 = mfma32(vf[2 * s + 1], pf[s], O1); }
;       __builtin_amdgcn_s_setprio(0);
; }
;       if (resc) { scale16(O0, alpha); scale16(O1, alpha); }
;     }
;     if (kt + 1 < 32) put_stage(smem + ((kt + 1) & 1) * STG);
;     else if (has_next) put_stage(smem);
;     __syncthreads();
;     if (kt + 2 < 32) get_stage(kt + 2);
;     else if (kt == 30 && has_next) { gk += (nh - h) * 64; gv += (nh - h) * 64; get_stage(0); }
.LBB0_1489:
	ds_read_b128 v[70:73], v67 offset:13312
	ds_read_b128 v[74:77], v67 offset:13344
	ds_read_b128 v[132:135], v67 offset:19968
	ds_read_b128 v[154:157], v67 offset:20000
	ds_read_b128 v[158:161], v67 offset:13376
	ds_read_b128 v[162:165], v67 offset:13408
	ds_read_b128 v[166:169], v67 offset:20032
	ds_read_b128 v[170:173], v67 offset:20064
	ds_read_b128 v[174:177], v67 offset:13440
	ds_read_b128 v[178:181], v67 offset:13472
	ds_read_b128 v[196:199], v67 offset:20096
	ds_read_b128 v[200:203], v67 offset:20128
	s_setprio 1
	s_waitcnt lgkmcnt(8)
	v_mfma_f32_32x32x16_bf16 v[48:63], v[70:73], v[100:103], v[220:235]
	v_mfma_f32_32x32x16_bf16 v[32:47], v[132:135], v[100:103], v[220:235]
	v_mfma_f32_32x32x16_bf16 v[48:63], v[74:77], v[96:99], v[48:63]
	v_mfma_f32_32x32x16_bf16 v[32:47], v[154:157], v[96:99], v[32:47]
	s_waitcnt lgkmcnt(4)
	v_mfma_f32_32x32x16_bf16 v[48:63], v[158:161], v[92:95], v[48:63]
	v_mfma_f32_32x32x16_bf16 v[32:47], v[166:169], v[92:95], v[32:47]
	v_mfma_f32_32x32x16_bf16 v[48:63], v[162:165], v[88:91], v[48:63]
	v_mfma_f32_32x32x16_bf16 v[32:47], v[170:173], v[88:91], v[32:47]
	s_waitcnt lgkmcnt(0)
	v_mfma_f32_32x32x16_bf16 v[48:63], v[174:177], v[84:87], v[48:63]
	v_mfma_f32_32x32x16_bf16 v[32:47], v[196:199], v[84:87], v[32:47]
	v_mfma_f32_32x32x16_bf16 v[48:63], v[178:181], v[80:83], v[48:63]
	v_mfma_f32_32x32x16_bf16 v[32:47], v[200:203], v[80:83], v[32:47]
	s_setprio 0
	ds_read_b64_tr_b16 v[132:133], v68 offset:38912
	ds_read_b64_tr_b16 v[134:135], v68 offset:40448
	ds_read_b64_tr_b16 v[156:157], v68 offset:40512
	ds_read_b64_tr_b16 v[154:155], v68 offset:38976
	ds_read_b64_tr_b16 v[158:159], v68 offset:41984
	ds_read_b64_tr_b16 v[160:161], v68 offset:43520
	ds_read_b64_tr_b16 v[164:165], v68 offset:43584
	ds_read_b64_tr_b16 v[162:163], v68 offset:42048
	ds_read_b64_tr_b16 v[166:167], v68 offset:45056
	ds_read_b64_tr_b16 v[168:169], v68 offset:46592
	ds_read_b64_tr_b16 v[172:173], v68 offset:46656
	ds_read_b64_tr_b16 v[170:171], v68 offset:45120
	ds_read_b64_tr_b16 v[174:175], v68 offset:48128
	ds_read_b64_tr_b16 v[176:177], v68 offset:49664
	ds_read_b64_tr_b16 v[180:181], v68 offset:49728
	ds_read_b64_tr_b16 v[178:179], v68 offset:48192
	v_exp_f32_e32 v40, v40
	v_exp_f32_e32 v41, v41
	v_exp_f32_e32 v42, v42
	v_exp_f32_e32 v43, v43
	v_exp_f32_e32 v44, v44
	v_exp_f32_e32 v45, v45
	v_exp_f32_e32 v46, v46
	v_exp_f32_e32 v47, v47
	v_exp_f32_e32 v48, v48
	v_exp_f32_e32 v49, v49
	v_exp_f32_e32 v50, v50
	v_exp_f32_e32 v51, v51
	v_exp_f32_e32 v52, v52
	v_exp_f32_e32 v53, v53
	v_exp_f32_e32 v54, v54
	v_exp_f32_e32 v55, v55
	v_exp_f32_e32 v56, v56
	v_exp_f32_e32 v57, v57
	v_exp_f32_e32 v58, v58
	v_exp_f32_e32 v59, v59
	v_exp_f32_e32 v60, v60
	v_exp_f32_e32 v61, v61
	v_exp_f32_e32 v62, v62
	v_exp_f32_e32 v63, v63
	v_exp_f32_e32 v67, v32
	v_exp_f32_e32 v69, v33
	v_exp_f32_e32 v70, v34
	v_exp_f32_e32 v71, v35
	v_exp_f32_e32 v36, v36
	v_exp_f32_e32 v37, v37
	v_exp_f32_e32 v38, v38
	v_exp_f32_e32 v39, v39
	v_cvt_pk_bf16_f32 v32, v40, v41
	v_cvt_pk_bf16_f32 v33, v42, v43
	v_cvt_pk_bf16_f32 v34, v44, v45
	v_cvt_pk_bf16_f32 v35, v46, v47
	v_cvt_pk_bf16_f32 v72, v67, v69
	v_cvt_pk_bf16_f32 v73, v70, v71
	v_cvt_pk_bf16_f32 v74, v36, v37
	v_cvt_pk_bf16_f32 v75, v38, v39
	v_cvt_pk_bf16_f32 v76, v56, v57
	v_cvt_pk_bf16_f32 v77, v58, v59
	v_cvt_pk_bf16_f32 v78, v60, v61
	v_cvt_pk_bf16_f32 v79, v62, v63
	v_cvt_pk_bf16_f32 v196, v48, v49
	v_cvt_pk_bf16_f32 v197, v50, v51
	v_cvt_pk_bf16_f32 v198, v52, v53
	v_cvt_pk_bf16_f32 v199, v54, v55
	s_setprio 1
	s_waitcnt lgkmcnt(8)
	v_mfma_f32_32x32x16_bf16 v[16:31], v[132:135], v[196:199], v[16:31]
	v_mfma_f32_32x32x16_bf16 v[0:15], v[154:157], v[196:199], v[0:15]
	v_mfma_f32_32x32x16_bf16 v[16:31], v[158:161], v[76:79], v[16:31]
	v_mfma_f32_32x32x16_bf16 v[0:15], v[162:165], v[76:79], v[0:15]
	s_waitcnt lgkmcnt(0)
	v_mfma_f32_32x32x16_bf16 v[16:31], v[166:169], v[72:75], v[16:31]
	v_mfma_f32_32x32x16_bf16 v[0:15], v[170:173], v[72:75], v[0:15]
	v_mfma_f32_32x32x16_bf16 v[16:31], v[174:177], v[32:35], v[16:31]
	v_mfma_f32_32x32x16_bf16 v[0:15], v[178:181], v[32:35], v[0:15]
	s_setprio 0
	s_bitcmp1_b32 s18, 0
	s_cselect_b32 s16, 0xc800, 0
	s_add_i32 s16, s16, 0
	v_add3_u32 v32, s16, v142, v138
	v_add3_u32 v33, s16, v139, v138
	s_waitcnt vmcnt(4)
	ds_write_b128 v32, v[104:107]
	s_waitcnt vmcnt(2)
	ds_write_b128 v33, v[108:111] offset:26624
	s_waitcnt vmcnt(2)
	ds_write_b128 v32, v[112:115] offset:13312
	s_waitcnt vmcnt(1)
	ds_write_b128 v33, v[116:119] offset:38912
	v_add3_u32 v32, s16, v143, v146
	s_cmp_gt_u32 s19, 29
	s_mov_b64 s[16:17], -1
	s_waitcnt vmcnt(0)
	ds_write_b128 v32, v[120:123] offset:128
	s_waitcnt lgkmcnt(0)
	s_barrier
	s_cbranch_scc0 .LBB0_1493
	s_cmp_lg_u32 s12, 0x410000
	s_cselect_b64 s[16:17], -1, 0
	s_xor_b64 s[20:21], s[10:11], -1
	s_or_b64 s[16:17], s[20:21], s[16:17]
	s_and_b64 vcc, exec, s[16:17]
	s_cbranch_vccnz .LBB0_1492
	v_lshl_add_u64 v[32:33], v[128:129], 0, s[14:15]
	v_add_co_u32_e32 v72, vcc, 0x10000, v32
	v_lshl_add_u64 v[34:35], v[130:131], 0, s[14:15]
	s_nop 0
	v_addc_co_u32_e32 v73, vcc, 0, v33, vcc
	global_load_dwordx4 v[104:107], v[32:33], off
	global_load_dwordx4 v[112:115], v[72:73], off
	v_add_co_u32_e32 v72, vcc, 0x10000, v34
	s_nop 1
	v_addc_co_u32_e32 v73, vcc, 0, v35, vcc
	global_load_dwordx4 v[108:111], v[34:35], off
	global_load_dwordx4 v[116:119], v[72:73], off
	global_load_dwordx4 v[120:123], v[126:127], off
	v_mov_b64_e32 v[128:129], v[32:33]
	v_mov_b64_e32 v[130:131], v[34:35]

; DI bool softmax_tile(f32x16& s0, f32x16& s1, float& m, float& l, float& alpha, bf16x8* pf, int lane, bool first, bool check) {
;     ...
;   float sum = 0.f;
; #pragma unroll
;   for (int i = 0; i < 16; ++i) { s0[i] = __builtin_amdgcn_exp2f(s0[i]); sum += s0[i]; }
; #pragma unroll
;   for (int i = 0; i < 16; ++i) { s1[i] = __builtin_amdgcn_exp2f(s1[i]); sum += s1[i]; }
;   l += sum;
; DI void attn_mla_unit(const Params& p, int b, int h, int qb, char* smem, bool pre, int nh, bool has_next) {
;     ...
;     if (kt + 2 < 32) get_stage(kt + 2);
;     else if (kt == 30 && has_next) { gk += (nh - h) * 64; gv += (nh - h) * 64; get_stage(0); }
;   }
.LBB0_1495:
	v_add_f32_e32 v48, v49, v48
	v_add_f32_e32 v48, v50, v48
	v_add_f32_e32 v48, v51, v48
	v_add_f32_e32 v48, v52, v48
	v_add_f32_e32 v48, v53, v48
	v_add_f32_e32 v48, v54, v48
	v_add_f32_e32 v48, v55, v48
	v_add_f32_e32 v48, v56, v48
	v_add_f32_e32 v48, v57, v48
	v_add_f32_e32 v48, v58, v48
	v_add_f32_e32 v48, v59, v48
	v_add_f32_e32 v48, v60, v48
	v_add_f32_e32 v48, v61, v48
	v_add_f32_e32 v48, v62, v48
	v_add_f32_e32 v48, v63, v48
	v_add_f32_e32 v48, v67, v48
	v_add_f32_e32 v48, v69, v48
	v_add_f32_e32 v48, v70, v48
	v_add_f32_e32 v48, v71, v48
	v_add_f32_e32 v36, v36, v48
	v_add_f32_e32 v36, v37, v36
	v_add_f32_e32 v36, v38, v36
	v_add_f32_e32 v36, v39, v36
	v_add_f32_e32 v36, v40, v36
	v_add_f32_e32 v36, v41, v36
	v_add_f32_e32 v36, v42, v36
	v_add_f32_e32 v36, v43, v36
	v_add_f32_e32 v36, v44, v36
	v_add_f32_e32 v36, v45, v36
	v_add_f32_e32 v36, v46, v36
	s_add_u32 s12, s12, 0x20000
	v_add_f32_e32 v36, v47, v36
	s_addc_u32 s13, s13, 0
	s_add_i32 s18, s18, 1
	s_mov_b64 s[16:17], 0x2000
	v_add_f32_e32 v153, v66, v36
	s_cmp_lg_u32 s12, 0x430000
	v_lshl_add_u64 v[64:65], v[64:65], 0, s[16:17]
	s_cbranch_scc0 .LBB0_1497
	s_branch .LBB0_1482
